# P6 loop: loader wave starts its MFMA block 6 MFMAs before the load-end barrier (low priority), on top of E3 + 4/4 DMA rebalance
# baseline (speedup 1.0000x reference)
.LBB0_1049:
	s_or_b32 s22, s88, 1
	s_lshl_b64 s[0:1], s[22:23], 7
	s_add_u32 s38, s6, s0
	s_addc_u32 s39, s7, s1
	s_add_i32 s22, s88, 2
	s_lshl_b64 s[0:1], s[22:23], 7
	s_add_u32 s62, s6, s0
	s_addc_u32 s63, s7, s1
	s_and_b64 s[2:3], s[28:29], exec
	s_cselect_b32 s3, s63, s77
	s_cselect_b32 s2, s62, s58
	s_add_u32 s62, s86, s0
	s_addc_u32 s63, s87, s1
	s_and_b64 s[0:1], s[28:29], exec
	s_cselect_b32 s29, s63, s93
	s_cselect_b32 s28, s62, s89
	s_add_i32 s62, 0, 0x10000
	v_add_u32_e32 v145, s62, v142
	s_add_i32 s63, 0, 0x14000
	ds_read_b128 v[136:139], v145
	ds_read_b128 v[146:149], v145 offset:1024
	ds_read_b128 v[150:153], v145 offset:2048
	ds_read_b128 v[154:157], v145 offset:3072
	v_add_u32_e32 v145, s63, v142
	ds_read_b128 v[158:161], v145
	ds_read_b128 v[162:165], v145 offset:1024
	ds_read_b128 v[166:169], v145 offset:2048
	ds_read_b128 v[170:173], v145 offset:3072
	s_add_u32 s0, s38, 0x80000
	s_addc_u32 s1, s39, 0
	s_mov_b32 m0, s30
	s_nop 0
	global_load_lds_dwordx4 v130, s[38:39]
	s_mov_b32 m0, s31
	s_nop 0
	global_load_lds_dwordx4 v132, s[38:39]
	s_add_i32 m0, s95, 0xc000
	ds_read_b128 v[174:177], v144
	ds_read_b128 v[178:181], v144 offset:1024
	ds_read_b128 v[182:185], v144 offset:2048
	ds_read_b128 v[186:189], v144 offset:3072
	ds_read_b128 v[190:193], v144 offset:4096
	ds_read_b128 v[194:197], v144 offset:5120
	ds_read_b128 v[198:201], v144 offset:6144
	ds_read_b128 v[226:229], v144 offset:7168
	global_load_lds_dwordx4 v130, s[0:1]
	s_add_i32 m0, s95, 0xe000
	s_nop 0
	global_load_lds_dwordx4 v132, s[0:1]
	s_waitcnt vmcnt(8)
	s_waitcnt lgkmcnt(0)
	v_mfma_f32_16x16x32_bf16 v[126:129], v[136:139], v[174:177], v[126:129]
	v_mfma_f32_16x16x32_bf16 v[114:117], v[150:153], v[174:177], v[114:117]
	v_mfma_f32_16x16x32_bf16 v[110:113], v[136:139], v[182:185], v[110:113]
	v_mfma_f32_16x16x32_bf16 v[98:101], v[150:153], v[182:185], v[98:101]
	v_mfma_f32_16x16x32_bf16 v[94:97], v[136:139], v[190:193], v[94:97]
	v_mfma_f32_16x16x32_bf16 v[82:85], v[150:153], v[190:193], v[82:85]
	s_barrier
	s_setprio 1
	v_mfma_f32_16x16x32_bf16 v[78:81], v[136:139], v[198:201], v[78:81]
	v_mfma_f32_16x16x32_bf16 v[66:69], v[150:153], v[198:201], v[66:69]
	v_mfma_f32_16x16x32_bf16 v[126:129], v[146:149], v[178:181], v[126:129]
	v_mfma_f32_16x16x32_bf16 v[114:117], v[154:157], v[178:181], v[114:117]
	v_mfma_f32_16x16x32_bf16 v[110:113], v[146:149], v[186:189], v[110:113]
	v_mfma_f32_16x16x32_bf16 v[98:101], v[154:157], v[186:189], v[98:101]
	v_mfma_f32_16x16x32_bf16 v[94:97], v[146:149], v[194:197], v[94:97]
	v_mfma_f32_16x16x32_bf16 v[82:85], v[154:157], v[194:197], v[82:85]
	v_mfma_f32_16x16x32_bf16 v[78:81], v[146:149], v[226:229], v[78:81]
	v_mfma_f32_16x16x32_bf16 v[66:69], v[154:157], v[226:229], v[66:69]
	v_mfma_f32_16x16x32_bf16 v[122:125], v[158:161], v[174:177], v[122:125]
	v_mfma_f32_16x16x32_bf16 v[118:121], v[166:169], v[174:177], v[118:121]
	v_mfma_f32_16x16x32_bf16 v[106:109], v[158:161], v[182:185], v[106:109]
	v_mfma_f32_16x16x32_bf16 v[102:105], v[166:169], v[182:185], v[102:105]
	v_mfma_f32_16x16x32_bf16 v[90:93], v[158:161], v[190:193], v[90:93]
	v_mfma_f32_16x16x32_bf16 v[86:89], v[166:169], v[190:193], v[86:89]
	v_mfma_f32_16x16x32_bf16 v[74:77], v[158:161], v[198:201], v[74:77]
	v_mfma_f32_16x16x32_bf16 v[70:73], v[166:169], v[198:201], v[70:73]
	v_mfma_f32_16x16x32_bf16 v[122:125], v[162:165], v[178:181], v[122:125]
	v_mfma_f32_16x16x32_bf16 v[118:121], v[170:173], v[178:181], v[118:121]
	v_mfma_f32_16x16x32_bf16 v[106:109], v[162:165], v[186:189], v[106:109]
	v_mfma_f32_16x16x32_bf16 v[102:105], v[170:173], v[186:189], v[102:105]
	v_mfma_f32_16x16x32_bf16 v[90:93], v[162:165], v[194:197], v[90:93]
	v_mfma_f32_16x16x32_bf16 v[86:89], v[170:173], v[194:197], v[86:89]
	v_mfma_f32_16x16x32_bf16 v[74:77], v[162:165], v[226:229], v[74:77]
	v_mfma_f32_16x16x32_bf16 v[70:73], v[170:173], v[226:229], v[70:73]
	s_setprio 0
	s_barrier
	s_add_i32 s0, s62, s75
	v_lshl_add_u64 v[206:207], s[28:29], 0, v[202:203]
	s_mov_b32 m0, s0
	ds_read_b128 v[174:177], v144 offset:16384
	ds_read_b128 v[178:181], v144 offset:17408
	ds_read_b128 v[182:185], v144 offset:18432
	ds_read_b128 v[186:189], v144 offset:19456
	ds_read_b128 v[190:193], v144 offset:20480
	ds_read_b128 v[194:197], v144 offset:21504
	ds_read_b128 v[198:201], v144 offset:22528
	ds_read_b128 v[226:229], v144 offset:23552
	global_load_lds_dwordx4 v[206:207], off
	s_add_i32 m0, s0, 0x2000
	s_add_u32 s0, s28, 0x80000
	v_lshl_add_u64 v[230:231], s[28:29], 0, v[134:135]
	s_addc_u32 s1, s29, 0
	s_add_i32 s38, s63, s75
	global_load_lds_dwordx4 v[230:231], off
	v_lshl_add_u64 v[232:233], s[0:1], 0, v[202:203]
	s_mov_b32 m0, s38
	s_nop 0
	global_load_lds_dwordx4 v[232:233], off
	v_lshl_add_u64 v[232:233], s[0:1], 0, v[134:135]
	s_add_i32 m0, s38, 0x2000
	s_nop 0
	global_load_lds_dwordx4 v[232:233], off
	s_waitcnt vmcnt(6)
	s_waitcnt lgkmcnt(0)
	v_mfma_f32_16x16x32_bf16 v[62:65], v[136:139], v[174:177], v[62:65]
	v_mfma_f32_16x16x32_bf16 v[50:53], v[150:153], v[174:177], v[50:53]
	v_mfma_f32_16x16x32_bf16 v[46:49], v[136:139], v[182:185], v[46:49]
	v_mfma_f32_16x16x32_bf16 v[34:37], v[150:153], v[182:185], v[34:37]
	v_mfma_f32_16x16x32_bf16 v[30:33], v[136:139], v[190:193], v[30:33]
	v_mfma_f32_16x16x32_bf16 v[18:21], v[150:153], v[190:193], v[18:21]
	s_barrier
	s_setprio 1
	v_mfma_f32_16x16x32_bf16 v[14:17], v[136:139], v[198:201], v[14:17]
	v_mfma_f32_16x16x32_bf16 v[6:9], v[150:153], v[198:201], v[6:9]
	v_mfma_f32_16x16x32_bf16 v[62:65], v[146:149], v[178:181], v[62:65]
	v_mfma_f32_16x16x32_bf16 v[50:53], v[154:157], v[178:181], v[50:53]
	v_mfma_f32_16x16x32_bf16 v[46:49], v[146:149], v[186:189], v[46:49]
	v_mfma_f32_16x16x32_bf16 v[34:37], v[154:157], v[186:189], v[34:37]
	v_mfma_f32_16x16x32_bf16 v[30:33], v[146:149], v[194:197], v[30:33]
	v_mfma_f32_16x16x32_bf16 v[18:21], v[154:157], v[194:197], v[18:21]
	v_mfma_f32_16x16x32_bf16 v[14:17], v[146:149], v[226:229], v[14:17]
	v_mfma_f32_16x16x32_bf16 v[6:9], v[154:157], v[226:229], v[6:9]
	v_mfma_f32_16x16x32_bf16 v[58:61], v[158:161], v[174:177], v[58:61]
	v_mfma_f32_16x16x32_bf16 v[54:57], v[166:169], v[174:177], v[54:57]
	v_mfma_f32_16x16x32_bf16 v[42:45], v[158:161], v[182:185], v[42:45]
	v_mfma_f32_16x16x32_bf16 v[38:41], v[166:169], v[182:185], v[38:41]
	v_mfma_f32_16x16x32_bf16 v[26:29], v[158:161], v[190:193], v[26:29]
	v_mfma_f32_16x16x32_bf16 v[22:25], v[166:169], v[190:193], v[22:25]
	v_mfma_f32_16x16x32_bf16 v[10:13], v[158:161], v[198:201], v[10:13]
	v_mfma_f32_16x16x32_bf16 v[2:5], v[166:169], v[198:201], v[2:5]
	v_mfma_f32_16x16x32_bf16 v[58:61], v[162:165], v[178:181], v[58:61]
	v_mfma_f32_16x16x32_bf16 v[54:57], v[170:173], v[178:181], v[54:57]
	v_mfma_f32_16x16x32_bf16 v[42:45], v[162:165], v[186:189], v[42:45]
	v_mfma_f32_16x16x32_bf16 v[38:41], v[170:173], v[186:189], v[38:41]
	v_mfma_f32_16x16x32_bf16 v[26:29], v[162:165], v[194:197], v[26:29]
	v_mfma_f32_16x16x32_bf16 v[22:25], v[170:173], v[194:197], v[22:25]
	v_mfma_f32_16x16x32_bf16 v[10:13], v[162:165], v[226:229], v[10:13]
	v_mfma_f32_16x16x32_bf16 v[2:5], v[170:173], v[226:229], v[2:5]
	s_setprio 0
	s_barrier
	s_add_i32 s38, 0, 0x18000
	v_add_u32_e32 v145, s38, v142
	s_add_i32 s39, 0, 0x1c000
	ds_read_b128 v[136:139], v145
	ds_read_b128 v[146:149], v145 offset:1024
	ds_read_b128 v[150:153], v145 offset:2048
	ds_read_b128 v[154:157], v145 offset:3072
	v_add_u32_e32 v145, s39, v142
	ds_read_b128 v[158:161], v145
	ds_read_b128 v[162:165], v145 offset:1024
	ds_read_b128 v[166:169], v145 offset:2048
	ds_read_b128 v[170:173], v145 offset:3072
	s_add_u32 s0, s2, 0x80000
	s_addc_u32 s1, s3, 0
	s_mov_b32 m0, s95
	s_nop 0
	global_load_lds_dwordx4 v130, s[2:3]
	s_mov_b32 m0, s97
	s_nop 0
	global_load_lds_dwordx4 v132, s[2:3]
	s_mov_b32 m0, s46
	ds_read_b128 v[174:177], v144 offset:32768
	ds_read_b128 v[178:181], v144 offset:33792
	ds_read_b128 v[182:185], v144 offset:34816
	ds_read_b128 v[186:189], v144 offset:35840
	ds_read_b128 v[190:193], v144 offset:36864
	ds_read_b128 v[194:197], v144 offset:37888
	ds_read_b128 v[198:201], v144 offset:38912
	ds_read_b128 v[226:229], v144 offset:39936
	global_load_lds_dwordx4 v130, s[0:1]
	s_mov_b32 m0, s48
	s_nop 0
	global_load_lds_dwordx4 v132, s[0:1]
	s_waitcnt vmcnt(8)
	s_waitcnt lgkmcnt(0)
	v_mfma_f32_16x16x32_bf16 v[126:129], v[136:139], v[174:177], v[126:129]
	v_mfma_f32_16x16x32_bf16 v[114:117], v[150:153], v[174:177], v[114:117]
	v_mfma_f32_16x16x32_bf16 v[110:113], v[136:139], v[182:185], v[110:113]
	v_mfma_f32_16x16x32_bf16 v[98:101], v[150:153], v[182:185], v[98:101]
	v_mfma_f32_16x16x32_bf16 v[94:97], v[136:139], v[190:193], v[94:97]
	v_mfma_f32_16x16x32_bf16 v[82:85], v[150:153], v[190:193], v[82:85]
	s_barrier
	s_setprio 1
	v_mfma_f32_16x16x32_bf16 v[78:81], v[136:139], v[198:201], v[78:81]
	v_mfma_f32_16x16x32_bf16 v[66:69], v[150:153], v[198:201], v[66:69]
	v_mfma_f32_16x16x32_bf16 v[126:129], v[146:149], v[178:181], v[126:129]
	v_mfma_f32_16x16x32_bf16 v[114:117], v[154:157], v[178:181], v[114:117]
	v_mfma_f32_16x16x32_bf16 v[110:113], v[146:149], v[186:189], v[110:113]
	v_mfma_f32_16x16x32_bf16 v[98:101], v[154:157], v[186:189], v[98:101]
	v_mfma_f32_16x16x32_bf16 v[94:97], v[146:149], v[194:197], v[94:97]
	v_mfma_f32_16x16x32_bf16 v[82:85], v[154:157], v[194:197], v[82:85]
	v_mfma_f32_16x16x32_bf16 v[78:81], v[146:149], v[226:229], v[78:81]
	v_mfma_f32_16x16x32_bf16 v[66:69], v[154:157], v[226:229], v[66:69]
	v_mfma_f32_16x16x32_bf16 v[122:125], v[158:161], v[174:177], v[122:125]
	v_mfma_f32_16x16x32_bf16 v[118:121], v[166:169], v[174:177], v[118:121]
	v_mfma_f32_16x16x32_bf16 v[106:109], v[158:161], v[182:185], v[106:109]
	v_mfma_f32_16x16x32_bf16 v[102:105], v[166:169], v[182:185], v[102:105]
	v_mfma_f32_16x16x32_bf16 v[90:93], v[158:161], v[190:193], v[90:93]
	v_mfma_f32_16x16x32_bf16 v[86:89], v[166:169], v[190:193], v[86:89]
	v_mfma_f32_16x16x32_bf16 v[74:77], v[158:161], v[198:201], v[74:77]
	v_mfma_f32_16x16x32_bf16 v[70:73], v[166:169], v[198:201], v[70:73]
	v_mfma_f32_16x16x32_bf16 v[122:125], v[162:165], v[178:181], v[122:125]
	v_mfma_f32_16x16x32_bf16 v[118:121], v[170:173], v[178:181], v[118:121]
	v_mfma_f32_16x16x32_bf16 v[106:109], v[162:165], v[186:189], v[106:109]
	v_mfma_f32_16x16x32_bf16 v[102:105], v[170:173], v[186:189], v[102:105]
	v_mfma_f32_16x16x32_bf16 v[90:93], v[162:165], v[194:197], v[90:93]
	v_mfma_f32_16x16x32_bf16 v[86:89], v[170:173], v[194:197], v[86:89]
	v_mfma_f32_16x16x32_bf16 v[74:77], v[162:165], v[226:229], v[74:77]
	v_mfma_f32_16x16x32_bf16 v[70:73], v[170:173], v[226:229], v[70:73]
	s_setprio 0
	s_barrier
	s_add_i32 s0, s38, s75
	v_lshl_add_u64 v[206:207], v[206:207], 0, s[42:43]
	s_mov_b32 m0, s0
	ds_read_b128 v[174:177], v144 offset:49152
	ds_read_b128 v[178:181], v144 offset:50176
	ds_read_b128 v[182:185], v144 offset:51200
	ds_read_b128 v[186:189], v144 offset:52224
	ds_read_b128 v[190:193], v144 offset:53248
	ds_read_b128 v[194:197], v144 offset:54272
	ds_read_b128 v[198:201], v144 offset:55296
	ds_read_b128 v[226:229], v144 offset:56320
	global_load_lds_dwordx4 v[206:207], off
	s_add_i32 m0, s0, 0x2000
	s_add_u32 s0, s28, 0x80080
	v_lshl_add_u64 v[206:207], v[230:231], 0, s[42:43]
	s_addc_u32 s1, s29, 0
	s_add_i32 s2, s39, s75
	global_load_lds_dwordx4 v[206:207], off
	v_lshl_add_u64 v[206:207], s[0:1], 0, v[202:203]
	s_mov_b32 m0, s2
	s_nop 0
	global_load_lds_dwordx4 v[206:207], off
	v_lshl_add_u64 v[206:207], s[0:1], 0, v[134:135]
	s_add_i32 m0, s2, 0x2000
	s_nop 0
	global_load_lds_dwordx4 v[206:207], off
	s_waitcnt vmcnt(6)
	s_waitcnt lgkmcnt(0)
	v_mfma_f32_16x16x32_bf16 v[62:65], v[136:139], v[174:177], v[62:65]
	v_mfma_f32_16x16x32_bf16 v[50:53], v[150:153], v[174:177], v[50:53]
	v_mfma_f32_16x16x32_bf16 v[46:49], v[136:139], v[182:185], v[46:49]
	v_mfma_f32_16x16x32_bf16 v[34:37], v[150:153], v[182:185], v[34:37]
	v_mfma_f32_16x16x32_bf16 v[30:33], v[136:139], v[190:193], v[30:33]
	v_mfma_f32_16x16x32_bf16 v[18:21], v[150:153], v[190:193], v[18:21]
	s_barrier
	s_setprio 1
	v_mfma_f32_16x16x32_bf16 v[14:17], v[136:139], v[198:201], v[14:17]
	v_mfma_f32_16x16x32_bf16 v[6:9], v[150:153], v[198:201], v[6:9]
	v_mfma_f32_16x16x32_bf16 v[62:65], v[146:149], v[178:181], v[62:65]
	v_mfma_f32_16x16x32_bf16 v[50:53], v[154:157], v[178:181], v[50:53]
	v_mfma_f32_16x16x32_bf16 v[46:49], v[146:149], v[186:189], v[46:49]
	v_mfma_f32_16x16x32_bf16 v[34:37], v[154:157], v[186:189], v[34:37]
	v_mfma_f32_16x16x32_bf16 v[30:33], v[146:149], v[194:197], v[30:33]
	v_mfma_f32_16x16x32_bf16 v[18:21], v[154:157], v[194:197], v[18:21]
	v_mfma_f32_16x16x32_bf16 v[14:17], v[146:149], v[226:229], v[14:17]
	v_mfma_f32_16x16x32_bf16 v[6:9], v[154:157], v[226:229], v[6:9]
	v_mfma_f32_16x16x32_bf16 v[58:61], v[158:161], v[174:177], v[58:61]
	v_mfma_f32_16x16x32_bf16 v[54:57], v[166:169], v[174:177], v[54:57]
	v_mfma_f32_16x16x32_bf16 v[42:45], v[158:161], v[182:185], v[42:45]
	v_mfma_f32_16x16x32_bf16 v[38:41], v[166:169], v[182:185], v[38:41]
	v_mfma_f32_16x16x32_bf16 v[26:29], v[158:161], v[190:193], v[26:29]
	v_mfma_f32_16x16x32_bf16 v[22:25], v[166:169], v[190:193], v[22:25]
	v_mfma_f32_16x16x32_bf16 v[10:13], v[158:161], v[198:201], v[10:13]
	v_mfma_f32_16x16x32_bf16 v[2:5], v[166:169], v[198:201], v[2:5]
	v_mfma_f32_16x16x32_bf16 v[58:61], v[162:165], v[178:181], v[58:61]
	v_mfma_f32_16x16x32_bf16 v[54:57], v[170:173], v[178:181], v[54:57]
	v_mfma_f32_16x16x32_bf16 v[42:45], v[162:165], v[186:189], v[42:45]
	v_mfma_f32_16x16x32_bf16 v[38:41], v[170:173], v[186:189], v[38:41]
	v_mfma_f32_16x16x32_bf16 v[26:29], v[162:165], v[194:197], v[26:29]
	v_mfma_f32_16x16x32_bf16 v[22:25], v[170:173], v[194:197], v[22:25]
	v_mfma_f32_16x16x32_bf16 v[10:13], v[162:165], v[226:229], v[10:13]
	v_mfma_f32_16x16x32_bf16 v[2:5], v[170:173], v[226:229], v[2:5]
	s_setprio 0
	s_barrier
	s_cmp_gt_u32 s88, 29
	s_mov_b32 s88, s22
	s_cbranch_scc1 .LBB0_1061
